# rsqrtf denormal-range scaling dropped at the eight row-scale sites of the FFN gate/up epilogue (arguments are mean square + eps, never denormal; bit-identical)
# baseline (speedup 1.0000x reference)
; __device__ __forceinline__ unsigned cvt_pk_bf16(float lo, float hi) { unsigned r; asm volatile("v_cvt_pk_bf16_f32 %0, %1, %2" : "=v"(r) : "v"(lo), "v"(hi)); return r; }
; __device__ __forceinline__ float frcp(float x) { return __builtin_amdgcn_rcpf(x); }
;     __device__ __forceinline__ void operator()(const f32x4 (&acc)[2][2][4][2], const Unit& u, int wr, int wc, int fr, int fq, const float (&epre)[8]) const {
;         const int row0 = u.pm * 256 + wr * 64 + fr, col0 = u.pn * 128 + wc * 32 + 8 * fq;
; #pragma unroll
;         for (int ai = 0; ai < 2; ++ai)
; #pragma unroll
;             for (int m = 0; m < 4; ++m) { const int row = row0 + ai * 128 + m * 16;
;                 const float rstd = rsqrtf(epre[ai * 4 + m] * (1.0f / DM) + EPS), c1 = -1.44269504f * rstd, c2 = rstd * rstd;
;                 f32x4 av[2];
; #pragma unroll
;                 for (int n = 0; n < 2; ++n) { const f32x4 g = acc[ai][0][m][n], t = g * c1; f32x4 e;
; #pragma unroll
;                     for (int j = 0; j < 4; ++j) e[j] = __builtin_amdgcn_exp2f(t[j]);
;                     const f32x4 d = e + 1.0f; f32x4 r;
; #pragma unroll
;                     for (int j = 0; j < 4; ++j) r[j] = frcp(d[j]);
;                     av[n] = (g * acc[ai][1][m][n]) * (r * c2); }
;                 u32x4 w; w.x = cvt_pk_bf16(av[0][0], av[0][1]); w.y = cvt_pk_bf16(av[0][2], av[0][3]); w.z = cvt_pk_bf16(av[1][0], av[1][1]); w.w = cvt_pk_bf16(av[1][2], av[1][3]);
;                 *(u32x4*)(ACT + (size_t)row * DFF + col0) = w; }
.Lpeel_x2_LBB0702:
	s_waitcnt vmcnt(0)
	v_fmamk_f32 v156, v156, 0x3a800000, v149
	v_pk_mul_f32 v[122:123], v[126:127], v[122:123]
	v_pk_mul_f32 v[120:121], v[124:125], v[120:121]
	v_rsq_f32_e32 v157, v156
	v_pk_mul_f32 v[114:115], v[118:119], v[114:115]
	v_pk_mul_f32 v[112:113], v[116:117], v[112:113]
	v_lshl_or_b32 v158, s22, 7, v145
	v_mul_f32_e32 v160, 0xbfb8aa3b, v157
	v_pk_mul_f32 v[166:167], v[160:161], v[124:125] op_sel_hi:[0,1]
	v_mul_f32_e32 v162, v157, v157
	v_exp_f32_e32 v157, v166
	v_pk_mul_f32 v[164:165], v[160:161], v[126:127] op_sel_hi:[0,1]
	v_exp_f32_e32 v161, v167
	v_exp_f32_e32 v163, v164
	v_exp_f32_e32 v167, v165
	v_add_f32_e32 v157, 1.0, v157
	v_rcp_f32_e32 v164, v157
	v_add_f32_e32 v157, 1.0, v161
	v_rcp_f32_e32 v165, v157
	v_add_f32_e32 v157, 1.0, v163
	v_rcp_f32_e32 v166, v157
	v_add_f32_e32 v157, 1.0, v167
	v_rcp_f32_e32 v167, v157
	v_pk_mul_f32 v[124:125], v[162:163], v[164:165] op_sel_hi:[0,1]
	v_pk_mul_f32 v[120:121], v[124:125], v[120:121]
	v_pk_mul_f32 v[124:125], v[160:161], v[118:119] op_sel_hi:[0,1]
	v_pk_mul_f32 v[126:127], v[162:163], v[166:167] op_sel_hi:[0,1]
	v_pk_mul_f32 v[122:123], v[126:127], v[122:123]
	v_pk_mul_f32 v[126:127], v[160:161], v[116:117] op_sel_hi:[0,1]
	v_exp_f32_e32 v126, v126
	v_exp_f32_e32 v127, v127
	v_exp_f32_e32 v157, v124
	v_exp_f32_e32 v160, v125
	v_add_f32_e32 v124, 1.0, v126
	v_add_f32_e32 v125, 1.0, v127
	v_add_f32_e32 v126, 1.0, v157
	v_add_f32_e32 v127, 1.0, v160
	v_rcp_f32_e32 v126, v126
	v_rcp_f32_e32 v127, v127
	v_rcp_f32_e32 v124, v124
	v_rcp_f32_e32 v125, v125
	v_lshl_add_u32 v156, s20, 8, v143
	v_pk_mul_f32 v[118:119], v[162:163], v[126:127] op_sel_hi:[0,1]
	v_pk_mul_f32 v[114:115], v[118:119], v[114:115]
	v_pk_mul_f32 v[116:117], v[162:163], v[124:125] op_sel_hi:[0,1]
	v_pk_mul_f32 v[112:113], v[116:117], v[112:113]
	v_cvt_pk_bf16_f32 v116, v120, v121
	v_cvt_pk_bf16_f32 v117, v122, v123
	v_ashrrev_i32_e32 v159, 31, v158
	v_cvt_pk_bf16_f32 v118, v112, v113
	v_cvt_pk_bf16_f32 v119, v114, v115
	v_fmamk_f32 v114, v155, 0x3a800000, v149
	v_mov_b64_e32 v[112:113], s[82:83]
	v_mad_i64_i32 v[120:121], s[20:21], v156, s41, v[112:113]
	v_rsq_f32_e32 v122, v114
	v_lshlrev_b64 v[114:115], 1, v[158:159]
	v_lshl_add_u64 v[120:121], v[120:121], 0, v[114:115]
	global_store_dwordx4 v[120:121], v[116:119], off
	v_pk_mul_f32 v[106:107], v[110:111], v[106:107]
	v_pk_mul_f32 v[104:105], v[108:109], v[104:105]
	v_mov_b32_e32 v117, v122
	v_mul_f32_e32 v116, 0xbfb8aa3b, v117
	v_pk_mul_f32 v[122:123], v[116:117], v[108:109] op_sel_hi:[0,1]
	v_mul_f32_e32 v118, v117, v117
	v_pk_mul_f32 v[120:121], v[116:117], v[110:111] op_sel_hi:[0,1]
	v_exp_f32_e32 v117, v122
	v_exp_f32_e32 v119, v123
	v_exp_f32_e32 v122, v120
	v_exp_f32_e32 v123, v121
	v_add_f32_e32 v117, 1.0, v117
	v_rcp_f32_e32 v120, v117
	v_add_f32_e32 v117, 1.0, v119
	v_rcp_f32_e32 v121, v117
	v_add_f32_e32 v117, 1.0, v122
	v_rcp_f32_e32 v122, v117
	v_add_f32_e32 v117, 1.0, v123
	v_rcp_f32_e32 v123, v117
	v_pk_mul_f32 v[108:109], v[118:119], v[120:121] op_sel_hi:[0,1]
	v_pk_mul_f32 v[104:105], v[108:109], v[104:105]
	v_pk_mul_f32 v[108:109], v[116:117], v[102:103] op_sel_hi:[0,1]
	v_pk_mul_f32 v[110:111], v[118:119], v[122:123] op_sel_hi:[0,1]
	v_pk_mul_f32 v[106:107], v[110:111], v[106:107]
	v_pk_mul_f32 v[110:111], v[116:117], v[100:101] op_sel_hi:[0,1]
	v_exp_f32_e32 v110, v110
	v_exp_f32_e32 v111, v111
	v_exp_f32_e32 v116, v108
	v_exp_f32_e32 v117, v109
	v_add_f32_e32 v108, 1.0, v110
	v_add_f32_e32 v109, 1.0, v111
	v_add_f32_e32 v110, 1.0, v116
	v_add_f32_e32 v111, 1.0, v117
	v_rcp_f32_e32 v108, v108
	v_rcp_f32_e32 v109, v109
	v_rcp_f32_e32 v110, v110
	v_rcp_f32_e32 v111, v111
	v_pk_mul_f32 v[98:99], v[102:103], v[98:99]
	v_pk_mul_f32 v[96:97], v[100:101], v[96:97]
	v_pk_mul_f32 v[100:101], v[118:119], v[108:109] op_sel_hi:[0,1]
	v_pk_mul_f32 v[102:103], v[118:119], v[110:111] op_sel_hi:[0,1]
	v_pk_mul_f32 v[102:103], v[102:103], v[98:99]
	v_pk_mul_f32 v[98:99], v[100:101], v[96:97]
	v_fmamk_f32 v101, v154, 0x3a800000, v149
	v_cvt_pk_bf16_f32 v96, v104, v105
	v_cvt_pk_bf16_f32 v97, v106, v107
	v_cvt_pk_bf16_f32 v98, v98, v99
	v_cvt_pk_bf16_f32 v99, v102, v103
	v_or_b32_e32 v100, 16, v156
	v_pk_mul_f32 v[90:91], v[94:95], v[90:91]
	v_rsq_f32_e32 v102, v101
	v_mad_i64_i32 v[100:101], s[20:21], v100, s41, v[112:113]
	v_lshl_add_u64 v[100:101], v[100:101], 0, v[114:115]
	global_store_dwordx4 v[100:101], v[96:99], off
	v_pk_mul_f32 v[88:89], v[92:93], v[88:89]
	v_pk_mul_f32 v[82:83], v[86:87], v[82:83]
	v_mov_b32_e32 v97, v102
	v_mul_f32_e32 v96, 0xbfb8aa3b, v97
	v_pk_mul_f32 v[102:103], v[96:97], v[92:93] op_sel_hi:[0,1]
	v_mul_f32_e32 v98, v97, v97
	v_pk_mul_f32 v[100:101], v[96:97], v[94:95] op_sel_hi:[0,1]
	v_exp_f32_e32 v97, v102
	v_exp_f32_e32 v99, v103
	v_exp_f32_e32 v102, v100
	v_exp_f32_e32 v103, v101
	v_add_f32_e32 v97, 1.0, v97
	v_rcp_f32_e32 v100, v97
	v_add_f32_e32 v97, 1.0, v99
	v_rcp_f32_e32 v101, v97
	v_add_f32_e32 v97, 1.0, v102
	v_rcp_f32_e32 v102, v97
	v_add_f32_e32 v97, 1.0, v103
	v_rcp_f32_e32 v103, v97
	v_pk_mul_f32 v[92:93], v[98:99], v[100:101] op_sel_hi:[0,1]
	v_pk_mul_f32 v[88:89], v[92:93], v[88:89]
	v_pk_mul_f32 v[92:93], v[96:97], v[86:87] op_sel_hi:[0,1]
	v_pk_mul_f32 v[94:95], v[98:99], v[102:103] op_sel_hi:[0,1]
	v_pk_mul_f32 v[90:91], v[94:95], v[90:91]
	v_pk_mul_f32 v[94:95], v[96:97], v[84:85] op_sel_hi:[0,1]
	v_exp_f32_e32 v94, v94
	v_exp_f32_e32 v95, v95
	v_exp_f32_e32 v96, v92
	v_exp_f32_e32 v97, v93
	v_add_f32_e32 v92, 1.0, v94
	v_add_f32_e32 v93, 1.0, v95
	v_add_f32_e32 v94, 1.0, v96
	v_add_f32_e32 v95, 1.0, v97
	v_rcp_f32_e32 v92, v92
	v_rcp_f32_e32 v93, v93
	v_rcp_f32_e32 v94, v94
; __device__ __forceinline__ unsigned cvt_pk_bf16(float lo, float hi) { unsigned r; asm volatile("v_cvt_pk_bf16_f32 %0, %1, %2" : "=v"(r) : "v"(lo), "v"(hi)); return r; }
; __device__ __forceinline__ float frcp(float x) { return __builtin_amdgcn_rcpf(x); }
;     __device__ __forceinline__ void operator()(const f32x4 (&acc)[2][2][4][2], const Unit& u, int wr, int wc, int fr, int fq, const float (&epre)[8]) const {
;     ...
;         for (int ai = 0; ai < 2; ++ai)
; #pragma unroll
;             for (int m = 0; m < 4; ++m) { const int row = row0 + ai * 128 + m * 16;
;                 const float rstd = rsqrtf(epre[ai * 4 + m] * (1.0f / DM) + EPS), c1 = -1.44269504f * rstd, c2 = rstd * rstd;
;                 f32x4 av[2];
; #pragma unroll
;                 for (int n = 0; n < 2; ++n) { const f32x4 g = acc[ai][0][m][n], t = g * c1; f32x4 e;
; #pragma unroll
;                     for (int j = 0; j < 4; ++j) e[j] = __builtin_amdgcn_exp2f(t[j]);
;                     const f32x4 d = e + 1.0f; f32x4 r;
; #pragma unroll
;                     for (int j = 0; j < 4; ++j) r[j] = frcp(d[j]);
;                     av[n] = (g * acc[ai][1][m][n]) * (r * c2); }
;                 u32x4 w; w.x = cvt_pk_bf16(av[0][0], av[0][1]); w.y = cvt_pk_bf16(av[0][2], av[0][3]); w.z = cvt_pk_bf16(av[1][0], av[1][1]); w.w = cvt_pk_bf16(av[1][2], av[1][3]);
;                 *(u32x4*)(ACT + (size_t)row * DFF + col0) = w; }
	v_rcp_f32_e32 v95, v95
	v_pk_mul_f32 v[80:81], v[84:85], v[80:81]
	v_pk_mul_f32 v[84:85], v[98:99], v[92:93] op_sel_hi:[0,1]
	v_pk_mul_f32 v[74:75], v[78:79], v[74:75]
	v_pk_mul_f32 v[86:87], v[98:99], v[94:95] op_sel_hi:[0,1]
	v_pk_mul_f32 v[86:87], v[86:87], v[82:83]
	v_pk_mul_f32 v[82:83], v[84:85], v[80:81]
	v_fmamk_f32 v85, v153, 0x3a800000, v149
	v_cvt_pk_bf16_f32 v80, v88, v89
	v_cvt_pk_bf16_f32 v81, v90, v91
	v_cvt_pk_bf16_f32 v82, v82, v83
	v_cvt_pk_bf16_f32 v83, v86, v87
	v_or_b32_e32 v84, 32, v156
	v_pk_mul_f32 v[72:73], v[76:77], v[72:73]
	v_rsq_f32_e32 v86, v85
	v_mad_i64_i32 v[84:85], s[20:21], v84, s41, v[112:113]
	v_lshl_add_u64 v[84:85], v[84:85], 0, v[114:115]
	global_store_dwordx4 v[84:85], v[80:83], off
	v_pk_mul_f32 v[66:67], v[70:71], v[66:67]
	v_pk_mul_f32 v[64:65], v[68:69], v[64:65]
	v_mov_b32_e32 v81, v86
	v_mul_f32_e32 v80, 0xbfb8aa3b, v81
	v_pk_mul_f32 v[86:87], v[80:81], v[76:77] op_sel_hi:[0,1]
	v_mul_f32_e32 v82, v81, v81
	v_pk_mul_f32 v[84:85], v[80:81], v[78:79] op_sel_hi:[0,1]
	v_exp_f32_e32 v81, v86
	v_exp_f32_e32 v83, v87
	v_exp_f32_e32 v86, v84
	v_exp_f32_e32 v87, v85
	v_add_f32_e32 v81, 1.0, v81
	v_rcp_f32_e32 v84, v81
	v_add_f32_e32 v81, 1.0, v83
	v_rcp_f32_e32 v85, v81
	v_add_f32_e32 v81, 1.0, v86
	v_rcp_f32_e32 v86, v81
	v_add_f32_e32 v81, 1.0, v87
	v_rcp_f32_e32 v87, v81
	v_pk_mul_f32 v[76:77], v[82:83], v[84:85] op_sel_hi:[0,1]
	v_pk_mul_f32 v[72:73], v[76:77], v[72:73]
	v_pk_mul_f32 v[76:77], v[80:81], v[70:71] op_sel_hi:[0,1]
	v_pk_mul_f32 v[78:79], v[82:83], v[86:87] op_sel_hi:[0,1]
	v_pk_mul_f32 v[74:75], v[78:79], v[74:75]
	v_pk_mul_f32 v[78:79], v[80:81], v[68:69] op_sel_hi:[0,1]
	v_exp_f32_e32 v78, v78
	v_exp_f32_e32 v79, v79
	v_exp_f32_e32 v80, v76
	v_exp_f32_e32 v81, v77
	v_add_f32_e32 v76, 1.0, v78
	v_add_f32_e32 v77, 1.0, v79
	v_add_f32_e32 v78, 1.0, v80
	v_add_f32_e32 v79, 1.0, v81
	v_rcp_f32_e32 v76, v76
	v_rcp_f32_e32 v77, v77
	v_rcp_f32_e32 v78, v78
	v_rcp_f32_e32 v79, v79
	v_pk_mul_f32 v[58:59], v[62:63], v[58:59]
	v_pk_mul_f32 v[68:69], v[82:83], v[76:77] op_sel_hi:[0,1]
	v_pk_mul_f32 v[56:57], v[60:61], v[56:57]
	v_pk_mul_f32 v[70:71], v[82:83], v[78:79] op_sel_hi:[0,1]
	v_pk_mul_f32 v[70:71], v[70:71], v[66:67]
	v_pk_mul_f32 v[66:67], v[68:69], v[64:65]
	v_cvt_pk_bf16_f32 v64, v72, v73
	v_cvt_pk_bf16_f32 v65, v74, v75
	v_or_b32_e32 v68, 48, v156
	v_cvt_pk_bf16_f32 v66, v66, v67
	v_cvt_pk_bf16_f32 v67, v70, v71
	v_fmamk_f32 v70, v152, 0x3a800000, v149
	v_mad_i64_i32 v[68:69], s[20:21], v68, s41, v[112:113]
	s_nop 0
	v_rsq_f32_e32 v70, v70
	v_lshl_add_u64 v[68:69], v[68:69], 0, v[114:115]
	global_store_dwordx4 v[68:69], v[64:67], off
	v_pk_mul_f32 v[50:51], v[54:55], v[50:51]
	v_pk_mul_f32 v[48:49], v[52:53], v[48:49]
	v_mov_b32_e32 v66, v70
	v_add_u32_e32 v65, 0x80, v156
	v_mul_f32_e32 v64, 0xbfb8aa3b, v66
	v_pk_mul_f32 v[70:71], v[64:65], v[60:61] op_sel_hi:[0,1]
	v_exp_f32_e32 v67, v70
	v_pk_mul_f32 v[68:69], v[64:65], v[62:63] op_sel_hi:[0,1]
	v_exp_f32_e32 v70, v71
	v_exp_f32_e32 v71, v68
	v_exp_f32_e32 v72, v69
	v_add_f32_e32 v67, 1.0, v67
	v_rcp_f32_e32 v68, v67
	v_add_f32_e32 v67, 1.0, v70
	v_rcp_f32_e32 v69, v67
	v_add_f32_e32 v67, 1.0, v71
	v_rcp_f32_e32 v70, v67
	v_add_f32_e32 v67, 1.0, v72
	v_rcp_f32_e32 v71, v67
	v_mul_f32_e32 v66, v66, v66
	v_pk_mul_f32 v[60:61], v[66:67], v[68:69] op_sel_hi:[0,1]
	v_pk_mul_f32 v[56:57], v[60:61], v[56:57]
	v_pk_mul_f32 v[62:63], v[66:67], v[70:71] op_sel_hi:[0,1]
	v_pk_mul_f32 v[58:59], v[62:63], v[58:59]
	v_pk_mul_f32 v[60:61], v[64:65], v[54:55] op_sel_hi:[0,1]
	v_pk_mul_f32 v[62:63], v[64:65], v[52:53] op_sel_hi:[0,1]
	v_exp_f32_e32 v62, v62
	v_exp_f32_e32 v63, v63
	v_exp_f32_e32 v64, v60
	v_exp_f32_e32 v67, v61
	v_add_f32_e32 v60, 1.0, v62
	v_add_f32_e32 v61, 1.0, v63
	v_add_f32_e32 v62, 1.0, v64
	v_add_f32_e32 v63, 1.0, v67
	v_rcp_f32_e32 v60, v60
	v_rcp_f32_e32 v61, v61
	v_rcp_f32_e32 v62, v62
	v_rcp_f32_e32 v63, v63
	v_pk_mul_f32 v[42:43], v[46:47], v[42:43]
	v_pk_mul_f32 v[52:53], v[66:67], v[60:61] op_sel_hi:[0,1]
	v_pk_mul_f32 v[40:41], v[44:45], v[40:41]
	v_pk_mul_f32 v[54:55], v[66:67], v[62:63] op_sel_hi:[0,1]
	v_pk_mul_f32 v[54:55], v[54:55], v[50:51]
	v_pk_mul_f32 v[50:51], v[52:53], v[48:49]
	v_fmamk_f32 v52, v151, 0x3a800000, v149
	v_cvt_pk_bf16_f32 v48, v56, v57
	v_cvt_pk_bf16_f32 v49, v58, v59
	v_cvt_pk_bf16_f32 v50, v50, v51
	v_cvt_pk_bf16_f32 v51, v54, v55
	v_pk_mul_f32 v[34:35], v[38:39], v[34:35]
	s_nop 0
	v_rsq_f32_e32 v54, v52
	v_mad_i64_i32 v[52:53], s[20:21], v65, s41, v[112:113]
	v_lshl_add_u64 v[52:53], v[52:53], 0, v[114:115]
	global_store_dwordx4 v[52:53], v[48:51], off
	v_pk_mul_f32 v[32:33], v[36:37], v[32:33]
	v_pk_mul_f32 v[26:27], v[30:31], v[26:27]
	v_mov_b32_e32 v49, v54
	v_mul_f32_e32 v48, 0xbfb8aa3b, v49
	v_pk_mul_f32 v[54:55], v[48:49], v[44:45] op_sel_hi:[0,1]
	v_mul_f32_e32 v50, v49, v49
	v_pk_mul_f32 v[52:53], v[48:49], v[46:47] op_sel_hi:[0,1]
	v_exp_f32_e32 v49, v54
	v_exp_f32_e32 v51, v55
	v_exp_f32_e32 v54, v52
	v_exp_f32_e32 v55, v53
	v_add_f32_e32 v49, 1.0, v49
	v_rcp_f32_e32 v52, v49
	v_add_f32_e32 v49, 1.0, v51
	v_rcp_f32_e32 v53, v49
	v_add_f32_e32 v49, 1.0, v54
	v_rcp_f32_e32 v54, v49
	v_add_f32_e32 v49, 1.0, v55
	v_rcp_f32_e32 v55, v49
	v_pk_mul_f32 v[44:45], v[50:51], v[52:53] op_sel_hi:[0,1]
	v_pk_mul_f32 v[40:41], v[44:45], v[40:41]
	v_pk_mul_f32 v[44:45], v[48:49], v[38:39] op_sel_hi:[0,1]
; __device__ __forceinline__ unsigned cvt_pk_bf16(float lo, float hi) { unsigned r; asm volatile("v_cvt_pk_bf16_f32 %0, %1, %2" : "=v"(r) : "v"(lo), "v"(hi)); return r; }
; __device__ __forceinline__ float frcp(float x) { return __builtin_amdgcn_rcpf(x); }
;     __device__ __forceinline__ void preload(const Unit& u, int wr, int fr, float (&pre)[8]) const { const int row0 = u.pm * 256 + wr * 64 + fr;
; #pragma unroll
;         for (int ai = 0; ai < 2; ++ai)
; #pragma unroll
;             for (int m = 0; m < 4; ++m) pre[ai * 4 + m] = sumsq[row0 + ai * 128 + m * 16]; }
;     __device__ __forceinline__ void operator()(const f32x4 (&acc)[2][2][4][2], const Unit& u, int wr, int wc, int fr, int fq, const float (&epre)[8]) const {
;     ...
;         for (int ai = 0; ai < 2; ++ai)
; #pragma unroll
;             for (int m = 0; m < 4; ++m) { const int row = row0 + ai * 128 + m * 16;
;                 const float rstd = rsqrtf(epre[ai * 4 + m] * (1.0f / DM) + EPS), c1 = -1.44269504f * rstd, c2 = rstd * rstd;
;                 f32x4 av[2];
; #pragma unroll
;                 for (int n = 0; n < 2; ++n) { const f32x4 g = acc[ai][0][m][n], t = g * c1; f32x4 e;
; #pragma unroll
;                     for (int j = 0; j < 4; ++j) e[j] = __builtin_amdgcn_exp2f(t[j]);
;                     const f32x4 d = e + 1.0f; f32x4 r;
; #pragma unroll
;                     for (int j = 0; j < 4; ++j) r[j] = frcp(d[j]);
;                     av[n] = (g * acc[ai][1][m][n]) * (r * c2); }
;                 u32x4 w; w.x = cvt_pk_bf16(av[0][0], av[0][1]); w.y = cvt_pk_bf16(av[0][2], av[0][3]); w.z = cvt_pk_bf16(av[1][0], av[1][1]); w.w = cvt_pk_bf16(av[1][2], av[1][3]);
;                 *(u32x4*)(ACT + (size_t)row * DFF + col0) = w; }
	v_pk_mul_f32 v[46:47], v[50:51], v[54:55] op_sel_hi:[0,1]
	v_pk_mul_f32 v[42:43], v[46:47], v[42:43]
	v_pk_mul_f32 v[46:47], v[48:49], v[36:37] op_sel_hi:[0,1]
	v_exp_f32_e32 v46, v46
	v_exp_f32_e32 v47, v47
	v_exp_f32_e32 v48, v44
	v_exp_f32_e32 v49, v45
	v_add_f32_e32 v44, 1.0, v46
	v_add_f32_e32 v45, 1.0, v47
	v_add_f32_e32 v46, 1.0, v48
	v_add_f32_e32 v47, 1.0, v49
	v_rcp_f32_e32 v44, v44
	v_rcp_f32_e32 v45, v45
	v_rcp_f32_e32 v46, v46
	v_rcp_f32_e32 v47, v47
	v_pk_mul_f32 v[24:25], v[28:29], v[24:25]
	v_pk_mul_f32 v[36:37], v[50:51], v[44:45] op_sel_hi:[0,1]
	v_pk_mul_f32 v[18:19], v[22:23], v[18:19]
	v_pk_mul_f32 v[38:39], v[50:51], v[46:47] op_sel_hi:[0,1]
	v_pk_mul_f32 v[38:39], v[38:39], v[34:35]
	v_pk_mul_f32 v[34:35], v[36:37], v[32:33]
	v_fmamk_f32 v37, v150, 0x3a800000, v149
	v_cvt_pk_bf16_f32 v32, v40, v41
	v_cvt_pk_bf16_f32 v33, v42, v43
	v_cvt_pk_bf16_f32 v34, v34, v35
	v_cvt_pk_bf16_f32 v35, v38, v39
	v_add_u32_e32 v36, 0x90, v156
	v_pk_mul_f32 v[16:17], v[20:21], v[16:17]
	v_rsq_f32_e32 v38, v37
	v_mad_i64_i32 v[36:37], s[20:21], v36, s41, v[112:113]
	v_lshl_add_u64 v[36:37], v[36:37], 0, v[114:115]
	global_store_dwordx4 v[36:37], v[32:35], off
	v_pk_mul_f32 v[10:11], v[14:15], v[10:11]
	v_pk_mul_f32 v[8:9], v[12:13], v[8:9]
	v_mov_b32_e32 v33, v38
	v_mul_f32_e32 v32, 0xbfb8aa3b, v33
	v_pk_mul_f32 v[38:39], v[32:33], v[28:29] op_sel_hi:[0,1]
	v_mul_f32_e32 v34, v33, v33
	v_pk_mul_f32 v[36:37], v[32:33], v[30:31] op_sel_hi:[0,1]
	v_exp_f32_e32 v33, v38
	v_exp_f32_e32 v35, v39
	v_exp_f32_e32 v38, v36
	v_exp_f32_e32 v39, v37
	v_add_f32_e32 v33, 1.0, v33
	v_rcp_f32_e32 v36, v33
	v_add_f32_e32 v33, 1.0, v35
	v_rcp_f32_e32 v37, v33
	v_add_f32_e32 v33, 1.0, v38
	v_rcp_f32_e32 v38, v33
	v_add_f32_e32 v33, 1.0, v39
	v_rcp_f32_e32 v39, v33
	v_pk_mul_f32 v[28:29], v[34:35], v[36:37] op_sel_hi:[0,1]
	v_pk_mul_f32 v[24:25], v[28:29], v[24:25]
	v_pk_mul_f32 v[28:29], v[32:33], v[22:23] op_sel_hi:[0,1]
	v_pk_mul_f32 v[30:31], v[34:35], v[38:39] op_sel_hi:[0,1]
	v_pk_mul_f32 v[26:27], v[30:31], v[26:27]
	v_pk_mul_f32 v[30:31], v[32:33], v[20:21] op_sel_hi:[0,1]
	v_exp_f32_e32 v30, v30
	v_exp_f32_e32 v31, v31
	v_exp_f32_e32 v32, v28
	v_exp_f32_e32 v33, v29
	v_add_f32_e32 v28, 1.0, v30
	v_add_f32_e32 v29, 1.0, v31
	v_add_f32_e32 v30, 1.0, v32
	v_add_f32_e32 v31, 1.0, v33
	v_rcp_f32_e32 v28, v28
	v_rcp_f32_e32 v29, v29
	v_rcp_f32_e32 v30, v30
	v_rcp_f32_e32 v31, v31
	v_pk_mul_f32 v[2:3], v[6:7], v[2:3]
	v_pk_mul_f32 v[20:21], v[34:35], v[28:29] op_sel_hi:[0,1]
	v_pk_mul_f32 v[0:1], v[4:5], v[0:1]
	v_pk_mul_f32 v[22:23], v[34:35], v[30:31] op_sel_hi:[0,1]
	v_pk_mul_f32 v[22:23], v[22:23], v[18:19]
	v_pk_mul_f32 v[18:19], v[20:21], v[16:17]
	v_fmamk_f32 v21, v142, 0x3a800000, v149
	v_cvt_pk_bf16_f32 v16, v24, v25
	v_cvt_pk_bf16_f32 v17, v26, v27
	v_cvt_pk_bf16_f32 v18, v18, v19
	v_cvt_pk_bf16_f32 v19, v22, v23
	v_add_u32_e32 v20, 0xa0, v156
	s_nop 0
	v_rsq_f32_e32 v22, v21
	v_mad_i64_i32 v[20:21], s[20:21], v20, s41, v[112:113]
	v_lshl_add_u64 v[20:21], v[20:21], 0, v[114:115]
	global_store_dwordx4 v[20:21], v[16:19], off
	s_nop 1
	v_mov_b32_e32 v17, v22
	v_mul_f32_e32 v16, 0xbfb8aa3b, v17
	v_pk_mul_f32 v[22:23], v[16:17], v[12:13] op_sel_hi:[0,1]
	v_mul_f32_e32 v18, v17, v17
	v_pk_mul_f32 v[20:21], v[16:17], v[14:15] op_sel_hi:[0,1]
	v_exp_f32_e32 v17, v22
	v_exp_f32_e32 v19, v23
	v_exp_f32_e32 v22, v20
	v_exp_f32_e32 v23, v21
	v_add_f32_e32 v17, 1.0, v17
	v_rcp_f32_e32 v20, v17
	v_add_f32_e32 v17, 1.0, v19
	v_rcp_f32_e32 v21, v17
	v_add_f32_e32 v17, 1.0, v22
	v_rcp_f32_e32 v22, v17
	v_add_f32_e32 v17, 1.0, v23
	v_rcp_f32_e32 v23, v17
	v_pk_mul_f32 v[12:13], v[18:19], v[20:21] op_sel_hi:[0,1]
	v_pk_mul_f32 v[8:9], v[12:13], v[8:9]
	v_pk_mul_f32 v[12:13], v[16:17], v[6:7] op_sel_hi:[0,1]
	v_pk_mul_f32 v[14:15], v[18:19], v[22:23] op_sel_hi:[0,1]
	v_pk_mul_f32 v[10:11], v[14:15], v[10:11]
	v_pk_mul_f32 v[14:15], v[16:17], v[4:5] op_sel_hi:[0,1]
	v_exp_f32_e32 v14, v14
	v_exp_f32_e32 v15, v15
	v_exp_f32_e32 v16, v12
	v_exp_f32_e32 v17, v13
	v_add_f32_e32 v12, 1.0, v14
	v_add_f32_e32 v13, 1.0, v15
	v_add_f32_e32 v14, 1.0, v16
	v_add_f32_e32 v15, 1.0, v17
	v_rcp_f32_e32 v12, v12
	v_rcp_f32_e32 v13, v13
	v_rcp_f32_e32 v14, v14
	v_rcp_f32_e32 v15, v15
	s_and_b64 vcc, s[16:17], exec
	v_pk_mul_f32 v[4:5], v[18:19], v[12:13] op_sel_hi:[0,1]
	v_pk_mul_f32 v[6:7], v[18:19], v[14:15] op_sel_hi:[0,1]
	v_pk_mul_f32 v[6:7], v[6:7], v[2:3]
	v_pk_mul_f32 v[2:3], v[4:5], v[0:1]
	v_add_u32_e32 v4, 0xb0, v156
	v_mad_i64_i32 v[4:5], s[20:21], v4, s41, v[112:113]
	v_lshl_add_u64 v[4:5], v[4:5], 0, v[114:115]
	s_mov_b64 s[20:21], -1
	v_cvt_pk_bf16_f32 v0, v8, v9
	v_cvt_pk_bf16_f32 v1, v10, v11
	v_cvt_pk_bf16_f32 v2, v2, v3
	v_cvt_pk_bf16_f32 v3, v6, v7
	global_store_dwordx4 v[4:5], v[0:3], off
	s_cbranch_vccz .LBB0_695
	s_nop 0
	v_lshl_add_u32 v0, s12, 8, v143
	v_ashrrev_i32_e32 v1, 31, v0
	v_lshl_add_u64 v[0:1], v[0:1], 2, s[10:11]
	global_load_dword v156, v[0:1], off
	global_load_dword v155, v[0:1], off offset:64
	global_load_dword v154, v[0:1], off offset:128
	global_load_dword v153, v[0:1], off offset:192
	global_load_dword v152, v[0:1], off offset:512
	global_load_dword v151, v[0:1], off offset:576
	global_load_dword v150, v[0:1], off offset:640
	global_load_dword v142, v[0:1], off offset:704
	s_mov_b64 s[20:21], 0
	s_branch .LBB0_695
